# same as the previous build but the -max fill of the QK accumulators is done at the top of the tile iteration (before the LDS stage) instead of in front of the first MFMA
# speedup vs baseline: 1.0029x; 1.0029x over previous
;     ...
;     auto lstore = [&](int buf) { bf16_t* Kb = (bf16_t*)(lds + buf * BUFB); bf16_t* Vb = (bf16_t*)(lds + buf * BUFB + 64 * KSTR * 2);
; #pragma unroll
;         for (int i = 0; i < NKC; ++i) { const int e = tid + 512 * i, row = e / CPR, cc = e % CPR; *(u32x4*)(Kb + row * KSTR + 8 * cc) = kreg[i]; }
; #pragma unroll
;         for (int i = 0; i < 2; ++i) { const int e = tid + 512 * i, d = e >> 3, cc = e & 7; u32x2* q = (u32x2*)(Vb + d * VSTR + 8 * cc); q[0] = (u32x2){vreg[i].x, vreg[i].y}; q[1] = (u32x2){vreg[i].z, vreg[i].w}; } };
;     ...
;         for (int t = 0; t < ntiles; ++t) { const int cur = t & 1;
;             if (t + 1 < ntiles) lstore(cur ^ 1);
;             if (t + 2 < ntiles) gload(t + 2);
;             if (t <= tmax_w) compute((const bf16_t*)(lds + cur * BUFB), (const bf16_t*)(lds + cur * BUFB + 64 * KSTR * 2), t);
.LBB0_1907:
	v_mov_b32_e32 v80, v255
	v_mov_b32_e32 v81, v255
	v_mov_b32_e32 v82, v255
	v_mov_b32_e32 v83, v255
	v_mov_b32_e32 v84, v255
	v_mov_b32_e32 v85, v255
	v_mov_b32_e32 v86, v255
	v_mov_b32_e32 v87, v255
	v_mov_b32_e32 v88, v255
	v_mov_b32_e32 v89, v255
	v_mov_b32_e32 v90, v255
	v_mov_b32_e32 v91, v255
	v_mov_b32_e32 v92, v255
	v_mov_b32_e32 v93, v255
	v_mov_b32_e32 v94, v255
	v_mov_b32_e32 v95, v255
	v_mov_b32_e32 v96, v255
	v_mov_b32_e32 v97, v255
	v_mov_b32_e32 v98, v255
	v_mov_b32_e32 v99, v255
	v_mov_b32_e32 v100, v255
	v_mov_b32_e32 v101, v255
	v_mov_b32_e32 v102, v255
	v_mov_b32_e32 v103, v255
	v_mov_b32_e32 v104, v255
	v_mov_b32_e32 v105, v255
	v_mov_b32_e32 v106, v255
	v_mov_b32_e32 v107, v255
	v_mov_b32_e32 v108, v255
	v_mov_b32_e32 v109, v255
	v_mov_b32_e32 v110, v255
	v_mov_b32_e32 v111, v255
	s_add_i32 s18, s16, 0x81
	s_and_b32 s17, s18, 1
	s_add_i32 s0, s16, 0x82
	s_cmp_ge_u32 s0, s13
	s_cbranch_scc1 .LBB0_1913
	s_xor_b32 s0, s17, 1
	s_mul_i32 s0, s0, 0xa800
	s_add_i32 s0, s0, 0
	v_add3_u32 v0, s0, v210, v211
	s_waitcnt vmcnt(4)
	ds_write_b128 v0, v[160:163]
	v_add3_u32 v0, s0, v216, v217
	s_waitcnt vmcnt(3)
	ds_write_b128 v0, v[164:167]
	v_add3_u32 v0, s0, v218, v219
	s_waitcnt vmcnt(2)
	ds_write_b128 v0, v[168:171]
	v_lshl_add_u32 v0, v220, 1, s0
	v_add3_u32 v0, v0, v188, s89
	s_waitcnt vmcnt(1)
	ds_write2_b64 v0, v[172:173], v[174:175] offset1:1
	v_lshl_add_u32 v0, v221, 1, s0
	v_add3_u32 v0, v0, v188, s89
	s_waitcnt vmcnt(0)
	ds_write2_b64 v0, v[176:177], v[178:179] offset1:1
	s_add_i32 s0, s16, 0x83
	s_cmp_ge_u32 s0, s13
	s_cbranch_scc0 .LBB0_1914

; #define MFMA32(a, b, c) __builtin_amdgcn_mfma_f32_32x32x16_bf16((a), (b), (c), 0, 0, 0)
; DI float xhalf_max(float v) { const auto r = __builtin_amdgcn_permlane32_swap(__float_as_uint(v), __float_as_uint(v), false, false); return fmaxf(__uint_as_float(r[0]), __uint_as_float(r[1])); }
;     ...
; #pragma unroll
;         for (int ks = 0; ks < NKS; ++ks) { const bf16x8 a0 = *(const bf16x8*)(Kt + lr * KSTR + 16 * ks + 8 * hi), a1 = *(const bf16x8*)(Kt + (32 + lr) * KSTR + 16 * ks + 8 * hi);
;             bf16x8 qq;
;             if (QREG == 1) qq = qf[ks];
;             else if (QREG == 2) qq = 16 * ks < DN ? qf[ks < NQF ? ks : 0] : *(const bf16x8*)(qr_row + (16 * ks - DN) + 8 * hi);
;             else qq = 16 * ks < DN ? *(const bf16x8*)(qa_row + 16 * ks + 8 * hi) : qf[(16 * ks - DN) / 16 < NQF ? (16 * ks - DN) / 16 : 0];
;             s0 = MFMA32(a0, qq, s0); s1 = MFMA32(a1, qq, s1);
;             if ((ks & 3) == 3) __builtin_amdgcn_sched_barrier(0); }
;         if (t == 0) {
; #pragma unroll
;             for (int i = 0; i < 16; ++i) { if (i >= 8) s0[i] = -INFINITY; s1[i] = -INFINITY; } }
;         float mx = s0[0];
; #pragma unroll
;         for (int i = 1; i < 16; ++i) mx = fmaxf(mx, s0[i]);
; #pragma unroll
;         for (int i = 0; i < 16; ++i) mx = fmaxf(mx, s1[i]);
;         mx = xhalf_max(mx);
;         const float mnew = fmaxf(mrun, mx), alpha = __builtin_amdgcn_exp2f(mrun - mnew);
;         const bool resc = __builtin_amdgcn_ballot_w64(mnew != mrun) != 0ull; mrun = mnew;
.LBB0_1910:
	s_mul_i32 s17, s17, 0xa800
	s_add_i32 s0, s17, 0
	v_lshlrev_b32_e32 v0, 1, v186
	v_add3_u32 v0, s0, v189, v0
	ds_read_b128 v[2:5], v0
	ds_read_b128 v[6:9], v0 offset:12800
	ds_read_b128 v[10:13], v0 offset:32
	ds_read_b128 v[226:229], v0 offset:12832
	ds_read_b128 v[230:233], v0 offset:64
	ds_read_b128 v[238:241], v0 offset:12864
	v_add3_u32 v225, s0, v14, v222
	v_add_u32_e32 v225, 0x6400, v225
	v_add_u32_e32 v234, 0x1100, v225
	v_add_u32_e32 v235, 0x2200, v225
	v_add_u32_e32 v236, 0x3300, v225
	s_waitcnt lgkmcnt(5)
	v_mfma_f32_32x32x16_bf16 v[80:95], v[2:5], v[112:115], v[80:95]
	ds_read_b128 v[2:5], v0 offset:96
	s_waitcnt lgkmcnt(5)
	v_mfma_f32_32x32x16_bf16 v[96:111], v[6:9], v[112:115], v[96:111]
	ds_read_b128 v[6:9], v0 offset:12896
	s_waitcnt lgkmcnt(5)
	v_mfma_f32_32x32x16_bf16 v[80:95], v[10:13], v[116:119], v[80:95]
	ds_read_b128 v[10:13], v0 offset:128
	s_waitcnt lgkmcnt(5)
	v_mfma_f32_32x32x16_bf16 v[96:111], v[226:229], v[116:119], v[96:111]
	ds_read_b128 v[226:229], v0 offset:12928
	s_waitcnt lgkmcnt(5)
	v_mfma_f32_32x32x16_bf16 v[80:95], v[230:233], v[120:123], v[80:95]
	ds_read_b128 v[230:233], v0 offset:160
	s_waitcnt lgkmcnt(5)
	v_mfma_f32_32x32x16_bf16 v[96:111], v[238:241], v[120:123], v[96:111]
	ds_read_b128 v[238:241], v0 offset:12960
	s_waitcnt lgkmcnt(5)
	v_mfma_f32_32x32x16_bf16 v[80:95], v[2:5], v[124:127], v[80:95]
	ds_read_b128 v[2:5], v0 offset:192
	s_waitcnt lgkmcnt(5)
	v_mfma_f32_32x32x16_bf16 v[96:111], v[6:9], v[124:127], v[96:111]
	ds_read_b128 v[6:9], v0 offset:12992
	s_waitcnt lgkmcnt(5)
	v_mfma_f32_32x32x16_bf16 v[80:95], v[10:13], v[128:131], v[80:95]
	ds_read_b128 v[10:13], v0 offset:224
	s_waitcnt lgkmcnt(5)
	v_mfma_f32_32x32x16_bf16 v[96:111], v[226:229], v[128:131], v[96:111]
	ds_read_b128 v[226:229], v0 offset:13024
	s_waitcnt lgkmcnt(5)
	v_mfma_f32_32x32x16_bf16 v[80:95], v[230:233], v[132:135], v[80:95]
	ds_read_b128 v[230:233], v0 offset:256
	s_waitcnt lgkmcnt(5)
	v_mfma_f32_32x32x16_bf16 v[96:111], v[238:241], v[132:135], v[96:111]
	ds_read_b128 v[238:241], v0 offset:13056
	s_waitcnt lgkmcnt(5)
	v_mfma_f32_32x32x16_bf16 v[80:95], v[2:5], v[136:139], v[80:95]
	ds_read_b128 v[2:5], v0 offset:288
	s_waitcnt lgkmcnt(5)
	v_mfma_f32_32x32x16_bf16 v[96:111], v[6:9], v[136:139], v[96:111]
	ds_read_b128 v[6:9], v0 offset:13088
	s_waitcnt lgkmcnt(5)
	v_mfma_f32_32x32x16_bf16 v[80:95], v[10:13], v[140:143], v[80:95]
	ds_read_b128 v[10:13], v0 offset:320
	s_waitcnt lgkmcnt(5)
	v_mfma_f32_32x32x16_bf16 v[96:111], v[226:229], v[140:143], v[96:111]
	ds_read_b128 v[226:229], v0 offset:13120
	s_waitcnt lgkmcnt(5)
	v_mfma_f32_32x32x16_bf16 v[80:95], v[230:233], v[144:147], v[80:95]
	ds_read_b128 v[230:233], v0 offset:352
	s_waitcnt lgkmcnt(5)
	v_mfma_f32_32x32x16_bf16 v[96:111], v[238:241], v[144:147], v[96:111]
	ds_read_b128 v[238:241], v0 offset:13152
	s_waitcnt lgkmcnt(5)
	v_mfma_f32_32x32x16_bf16 v[80:95], v[2:5], v[148:151], v[80:95]
	ds_read2_b64 v[242:245], v225 offset1:2
	s_waitcnt lgkmcnt(5)
	v_mfma_f32_32x32x16_bf16 v[96:111], v[6:9], v[148:151], v[96:111]
	s_waitcnt lgkmcnt(4)
	v_mfma_f32_32x32x16_bf16 v[80:95], v[10:13], v[152:155], v[80:95]
	s_waitcnt lgkmcnt(3)
	v_mfma_f32_32x32x16_bf16 v[96:111], v[226:229], v[152:155], v[96:111]
	ds_read2_b64 v[226:229], v225 offset0:4 offset1:6
	s_waitcnt lgkmcnt(3)
	v_mfma_f32_32x32x16_bf16 v[80:95], v[230:233], v[156:159], v[80:95]
	ds_read2_b64 v[230:233], v225 offset0:8 offset1:10
	s_waitcnt lgkmcnt(3)
	v_mfma_f32_32x32x16_bf16 v[96:111], v[238:241], v[156:159], v[96:111]
	ds_read2_b64 v[238:241], v225 offset0:12 offset1:14
	s_nop 8
	v_max_f32_e32 v0, v81, v81
	v_max_f32_e32 v2, v80, v80
	v_max_f32_e32 v0, v2, v0
	v_max3_f32 v0, v0, v82, v83
	v_max3_f32 v0, v0, v84, v85
	v_max3_f32 v0, v0, v86, v87
	v_max3_f32 v0, v0, v88, v89
	v_max3_f32 v0, v0, v90, v91
	v_max3_f32 v0, v0, v92, v93
	v_max3_f32 v0, v0, v94, v95
	v_max3_f32 v0, v0, v96, v97
	v_max3_f32 v0, v0, v98, v99
	v_max3_f32 v0, v0, v100, v101
	v_max3_f32 v0, v0, v102, v103
	v_max3_f32 v0, v0, v104, v105
	v_max3_f32 v0, v0, v106, v107
	v_max3_f32 v0, v0, v108, v109
	v_max3_f32 v0, v0, v110, v111
	v_mov_b32_e32 v2, v0
	s_nop 1
	v_permlane32_swap_b32_e32 v0, v2
	v_max_f32_e32 v2, v0, v2
	v_cmp_lt_f32_e32 vcc, 0x41000000, v2
	s_cbranch_vccz .Lfz_fast
; DI float xhalf_max(float v) { const auto r = __builtin_amdgcn_permlane32_swap(__float_as_uint(v), __float_as_uint(v), false, false); return fmaxf(__uint_as_float(r[0]), __uint_as_float(r[1])); }
;     ...
;         float mx = s0[0];
; #pragma unroll
;         for (int i = 1; i < 16; ++i) mx = fmaxf(mx, s0[i]);
; #pragma unroll
;         for (int i = 0; i < 16; ++i) mx = fmaxf(mx, s1[i]);
;         mx = xhalf_max(mx);
;         const float mnew = fmaxf(mrun, mx), alpha = __builtin_amdgcn_exp2f(mrun - mnew);
;         const bool resc = __builtin_amdgcn_ballot_w64(mnew != mrun) != 0ull; mrun = mnew;
;         float ps = 0.f;
; #pragma unroll
;         for (int i = 0; i < 16; ++i) { s0[i] = __builtin_amdgcn_exp2f(s0[i] - mnew); s1[i] = __builtin_amdgcn_exp2f(s1[i] - mnew); ps += s0[i] + s1[i]; }
;         lrun = lrun * alpha + ps;
;         if (resc) {
; #pragma unroll
;             for (int d = 0; d < 4; ++d)
; #pragma unroll
;                 for (int i = 0; i < 16; ++i) oacc[d][i] *= alpha; }
;         bf16x8 pf[4]; pf[0] = packs(s0, 0); pf[1] = packs(s0, 1); pf[2] = packs(s1, 0); pf[3] = packs(s1, 1);
	v_cndmask_b32_e32 v15, 0, v2, vcc
	v_sub_f32_e32 v0, 0, v15
	v_exp_f32_e32 v0, v0
	v_add_f32_e32 v224, v224, v15
	v_sub_f32_e32 v255, 0, v224
	v_pk_mul_f32 v[46:47], v[46:47], v[0:1] op_sel_hi:[1,0]
	v_pk_mul_f32 v[44:45], v[44:45], v[0:1] op_sel_hi:[1,0]
	v_pk_mul_f32 v[42:43], v[42:43], v[0:1] op_sel_hi:[1,0]
	v_pk_mul_f32 v[40:41], v[40:41], v[0:1] op_sel_hi:[1,0]
	v_pk_mul_f32 v[38:39], v[38:39], v[0:1] op_sel_hi:[1,0]
	v_pk_mul_f32 v[36:37], v[36:37], v[0:1] op_sel_hi:[1,0]
	v_pk_mul_f32 v[34:35], v[34:35], v[0:1] op_sel_hi:[1,0]
	v_pk_mul_f32 v[32:33], v[32:33], v[0:1] op_sel_hi:[1,0]
	v_pk_mul_f32 v[78:79], v[78:79], v[0:1] op_sel_hi:[1,0]
	v_pk_mul_f32 v[76:77], v[76:77], v[0:1] op_sel_hi:[1,0]
	v_pk_mul_f32 v[74:75], v[74:75], v[0:1] op_sel_hi:[1,0]
	v_pk_mul_f32 v[72:73], v[72:73], v[0:1] op_sel_hi:[1,0]
	v_pk_mul_f32 v[70:71], v[70:71], v[0:1] op_sel_hi:[1,0]
	v_pk_mul_f32 v[68:69], v[68:69], v[0:1] op_sel_hi:[1,0]
	v_pk_mul_f32 v[66:67], v[66:67], v[0:1] op_sel_hi:[1,0]
	v_pk_mul_f32 v[64:65], v[64:65], v[0:1] op_sel_hi:[1,0]
	v_pk_mul_f32 v[62:63], v[62:63], v[0:1] op_sel_hi:[1,0]
	v_pk_mul_f32 v[60:61], v[60:61], v[0:1] op_sel_hi:[1,0]
	v_pk_mul_f32 v[58:59], v[58:59], v[0:1] op_sel_hi:[1,0]
	v_pk_mul_f32 v[56:57], v[56:57], v[0:1] op_sel_hi:[1,0]
	v_pk_mul_f32 v[54:55], v[54:55], v[0:1] op_sel_hi:[1,0]
	v_pk_mul_f32 v[52:53], v[52:53], v[0:1] op_sel_hi:[1,0]
	v_pk_mul_f32 v[50:51], v[50:51], v[0:1] op_sel_hi:[1,0]
	v_pk_mul_f32 v[48:49], v[48:49], v[0:1] op_sel_hi:[1,0]
	v_pk_mul_f32 v[30:31], v[30:31], v[0:1] op_sel_hi:[1,0]
	v_pk_mul_f32 v[28:29], v[28:29], v[0:1] op_sel_hi:[1,0]
	v_pk_mul_f32 v[26:27], v[26:27], v[0:1] op_sel_hi:[1,0]
	v_pk_mul_f32 v[24:25], v[24:25], v[0:1] op_sel_hi:[1,0]
	v_pk_mul_f32 v[22:23], v[22:23], v[0:1] op_sel_hi:[1,0]
	v_pk_mul_f32 v[20:21], v[20:21], v[0:1] op_sel_hi:[1,0]
	v_pk_mul_f32 v[18:19], v[18:19], v[0:1] op_sel_hi:[1,0]
	v_pk_mul_f32 v[16:17], v[16:17], v[0:1] op_sel_hi:[1,0]
	v_sub_f32_e32 v2, v80, v15
	v_sub_f32_e32 v3, v96, v15
	v_exp_f32_e32 v2, v2
	v_exp_f32_e32 v3, v3
	v_sub_f32_e32 v5, v81, v15
	v_sub_f32_e32 v6, v97, v15
	v_exp_f32_e32 v5, v5
	v_exp_f32_e32 v6, v6
	v_add_f32_e32 v4, v2, v3
	v_add_f32_e32 v4, 0, v4
	v_sub_f32_e32 v8, v98, v15
	v_add_f32_e32 v7, v5, v6
	v_add_f32_e32 v4, v7, v4
	v_sub_f32_e32 v7, v82, v15
	v_exp_f32_e32 v7, v7
	v_exp_f32_e32 v8, v8
	v_sub_f32_e32 v10, v99, v15
	v_exp_f32_e32 v96, v10
	v_sub_f32_e32 v11, v100, v15
	v_add_f32_e32 v9, v7, v8
	v_add_f32_e32 v4, v9, v4
	v_sub_f32_e32 v9, v83, v15
	v_exp_f32_e32 v9, v9
	v_sub_f32_e32 v12, v101, v15
	v_sub_f32_e32 v13, v102, v15
	v_sub_f32_e32 v80, v103, v15
	v_add_f32_e32 v10, v9, v96
	v_add_f32_e32 v4, v10, v4
	v_sub_f32_e32 v10, v84, v15
	v_exp_f32_e32 v10, v10
	v_exp_f32_e32 v84, v11
	v_cvt_pk_bf16_f32 v81, v7, v9
	v_cvt_pk_bf16_f32 v7, v8, v96
	v_cvt_pk_bf16_f32 v6, v3, v6
	v_add_f32_e32 v11, v10, v84
	v_add_f32_e32 v4, v11, v4
	v_sub_f32_e32 v11, v85, v15
	v_exp_f32_e32 v11, v11
	v_exp_f32_e32 v85, v12
	v_cvt_pk_bf16_f32 v82, v10, v11
	v_add_f32_e32 v12, v11, v85
	v_add_f32_e32 v4, v12, v4
	v_sub_f32_e32 v12, v86, v15
	v_exp_f32_e32 v12, v12
	v_exp_f32_e32 v86, v13
	v_cvt_pk_bf16_f32 v8, v84, v85
	v_add_f32_e32 v13, v12, v86
	v_add_f32_e32 v4, v13, v4
	v_sub_f32_e32 v13, v87, v15
	v_exp_f32_e32 v13, v13
	v_exp_f32_e32 v87, v80
	v_cvt_pk_bf16_f32 v83, v12, v13
	v_add_f32_e32 v80, v13, v87
	v_add_f32_e32 v4, v80, v4
	v_sub_f32_e32 v80, v88, v15
	v_exp_f32_e32 v88, v80
	v_sub_f32_e32 v80, v104, v15
	v_exp_f32_e32 v97, v80
	v_cvt_pk_bf16_f32 v9, v86, v87
	v_add_f32_e32 v80, v88, v97
	v_add_f32_e32 v4, v80, v4
	v_sub_f32_e32 v80, v89, v15
	v_exp_f32_e32 v89, v80
	v_sub_f32_e32 v80, v105, v15
	v_exp_f32_e32 v98, v80
	v_cvt_pk_bf16_f32 v10, v88, v89
	v_add_f32_e32 v80, v89, v98
	v_add_f32_e32 v4, v80, v4
	v_sub_f32_e32 v80, v90, v15
	v_exp_f32_e32 v90, v80
	v_sub_f32_e32 v80, v106, v15
	v_exp_f32_e32 v99, v80
	s_nop 0
	v_add_f32_e32 v80, v90, v99
	v_add_f32_e32 v4, v80, v4
	v_sub_f32_e32 v80, v91, v15
	v_exp_f32_e32 v91, v80
	v_sub_f32_e32 v80, v107, v15
	v_exp_f32_e32 v100, v80
	v_cvt_pk_bf16_f32 v11, v90, v91
	v_add_f32_e32 v80, v91, v100
	v_add_f32_e32 v4, v80, v4
	v_sub_f32_e32 v80, v92, v15
	v_exp_f32_e32 v92, v80
	v_sub_f32_e32 v80, v108, v15
	v_exp_f32_e32 v101, v80
	v_cvt_pk_bf16_f32 v3, v99, v100
	v_add_f32_e32 v80, v92, v101
	v_add_f32_e32 v4, v80, v4
	v_sub_f32_e32 v80, v93, v15
	v_exp_f32_e32 v93, v80
	v_sub_f32_e32 v80, v109, v15
	v_exp_f32_e32 v102, v80
	v_cvt_pk_bf16_f32 v12, v92, v93
	v_add_f32_e32 v80, v93, v102
	v_add_f32_e32 v4, v80, v4
	v_sub_f32_e32 v80, v94, v15
	v_exp_f32_e32 v94, v80
	v_sub_f32_e32 v80, v110, v15
	v_exp_f32_e32 v103, v80
	s_nop 0
	v_add_f32_e32 v80, v94, v103
	v_add_f32_e32 v4, v80, v4
	v_sub_f32_e32 v80, v95, v15
	v_exp_f32_e32 v95, v80
	v_sub_f32_e32 v80, v111, v15
	v_exp_f32_e32 v104, v80
	v_cvt_pk_bf16_f32 v13, v94, v95
	v_add_f32_e32 v80, v95, v104
	v_add_f32_e32 v105, v80, v4
	v_fmac_f32_e32 v105, v223, v0
	s_branch .Lfz_join
